# plus: XNACK-replay s_nop pads removed between the retention item's back-to-back prefetch loads (removable hazard-pass pads under xnack-)
# speedup vs baseline: 1.0002x; 1.0002x over previous
; #define LAS __attribute__((address_space(3)))
; __device__ __forceinline__ unsigned pk2(float lo, float hi) { return pg8::cvt_pk_bf16(lo, hi); }
; __device__ __forceinline__ void ret_item(LAS unsigned char* lds, const bf16* proj, bf16* yout, int gv, int vloc, int hd, int dir) {
;     ...
;             LAS bf16* kt = KTW + c8 * LD + i0; LAS bf16* vt = VT + c8 * LD + i0;
; #pragma unroll
;             for (int m = 0; m < 4; ++m) {
;                 u32x2 we, wo;
;                 we.x = pk2(bflo(kraw[0][m]) * wl[0], bflo(kraw[1][m]) * wl[1]); we.y = pk2(bflo(kraw[2][m]) * wl[2], bflo(kraw[3][m]) * wl[3]);
;                 wo.x = pk2(bfhi(kraw[0][m]) * wl[0], bfhi(kraw[1][m]) * wl[1]); wo.y = pk2(bfhi(kraw[2][m]) * wl[2], bfhi(kraw[3][m]) * wl[3]);
;                 *(LAS u32x2*)(kt + (2 * m) * LD) = we; *(LAS u32x2*)(kt + (2 * m + 1) * LD) = wo;
;                 u32x2 ve, vo;
;                 ve.x = (vraw[0][m] & 0xffffu) | (vraw[1][m] << 16); ve.y = (vraw[2][m] & 0xffffu) | (vraw[3][m] << 16);
;                 vo.x = (vraw[0][m] >> 16) | (vraw[1][m] & 0xffff0000u); vo.y = (vraw[2][m] >> 16) | (vraw[3][m] & 0xffff0000u);
;                 *(LAS u32x2*)(vt + (2 * m) * LD) = ve; *(LAS u32x2*)(vt + (2 * m + 1) * LD) = vo;
;             }
;         }
;         bf16x8 qf[4];
; #pragma unroll
;         for (int ks = 0; ks < 4; ++ks) qf[ks] = __builtin_bit_cast(bf16x8, qraw[ks]);
;         if (c < 63) { const int ncc = dir ? cc - 1 : cc + 1; RET_LOAD(ncc); }
.LBB0_664:
	s_waitcnt vmcnt(11)
	v_lshlrev_b32_e32 v36, 16, v0
	s_waitcnt vmcnt(9)
	v_lshlrev_b32_e32 v37, 16, v8
	v_mul_f32_e32 v36, v142, v36
	v_mul_f32_e32 v37, v143, v37
	v_cvt_pk_bf16_f32 v36, v36, v37
	s_waitcnt vmcnt(7)
	v_lshlrev_b32_e32 v37, 16, v16
	s_waitcnt vmcnt(5)
	v_lshlrev_b32_e32 v38, 16, v24
	v_mul_f32_e32 v37, v144, v37
	v_mul_f32_e32 v38, v145, v38
	v_cvt_pk_bf16_f32 v37, v37, v38
	v_and_b32_e32 v38, 0xffff0000, v0
	v_and_b32_e32 v39, 0xffff0000, v8
	v_mul_f32_e32 v38, v142, v38
	v_mul_f32_e32 v39, v143, v39
	v_cvt_pk_bf16_f32 v38, v38, v39
	v_and_b32_e32 v39, 0xffff0000, v16
	v_and_b32_e32 v40, 0xffff0000, v24
	v_mul_f32_e32 v39, v144, v39
	v_mul_f32_e32 v40, v145, v40
	v_cvt_pk_bf16_f32 v39, v39, v40
	v_add_u32_e32 v40, 0x8800, v147
	ds_write2_b64 v40, v[36:37], v[38:39] offset1:34
	v_and_b32_e32 v36, 0xffff, v4
	v_and_b32_e32 v37, 0xffff, v20
	v_lshrrev_b32_e32 v38, 16, v4
	v_lshrrev_b32_e32 v39, 16, v20
	v_lshl_or_b32 v36, v12, 16, v36
	s_waitcnt vmcnt(4)
	v_lshl_or_b32 v37, v28, 16, v37
	v_and_or_b32 v38, v12, s33, v38
	v_and_or_b32 v39, v28, s33, v39
	ds_write2_b64 v148, v[36:37], v[38:39] offset1:34
	v_lshlrev_b32_e32 v36, 16, v1
	v_lshlrev_b32_e32 v37, 16, v9
	v_mul_f32_e32 v36, v142, v36
	v_mul_f32_e32 v37, v143, v37
	v_cvt_pk_bf16_f32 v36, v36, v37
	v_lshlrev_b32_e32 v37, 16, v17
	v_lshlrev_b32_e32 v38, 16, v25
	v_mul_f32_e32 v37, v144, v37
	v_mul_f32_e32 v38, v145, v38
	v_cvt_pk_bf16_f32 v37, v37, v38
	v_and_b32_e32 v38, 0xffff0000, v1
	v_and_b32_e32 v39, 0xffff0000, v9
	v_mul_f32_e32 v38, v142, v38
	v_mul_f32_e32 v39, v143, v39
	v_cvt_pk_bf16_f32 v38, v38, v39
	v_and_b32_e32 v39, 0xffff0000, v17
	v_mul_f32_e32 v39, v144, v39
	v_and_b32_e32 v41, 0xffff0000, v25
	v_mul_f32_e32 v41, v145, v41
	v_cvt_pk_bf16_f32 v39, v39, v41
	ds_write2_b64 v40, v[36:37], v[38:39] offset0:68 offset1:102
	v_and_b32_e32 v36, 0xffff, v5
	v_and_b32_e32 v37, 0xffff, v21
	v_lshrrev_b32_e32 v38, 16, v5
	v_lshrrev_b32_e32 v39, 16, v21
	v_lshl_or_b32 v36, v13, 16, v36
	v_lshl_or_b32 v37, v29, 16, v37
	v_and_or_b32 v38, v13, s33, v38
	v_and_or_b32 v39, v29, s33, v39
	ds_write2_b64 v148, v[36:37], v[38:39] offset0:68 offset1:102
	v_lshlrev_b32_e32 v36, 16, v2
	v_lshlrev_b32_e32 v37, 16, v10
	v_mul_f32_e32 v36, v142, v36
	v_mul_f32_e32 v37, v143, v37
	v_cvt_pk_bf16_f32 v36, v36, v37
	v_lshlrev_b32_e32 v37, 16, v18
	v_lshlrev_b32_e32 v38, 16, v26
	v_mul_f32_e32 v37, v144, v37
	v_mul_f32_e32 v38, v145, v38
	v_cvt_pk_bf16_f32 v37, v37, v38
	v_and_b32_e32 v38, 0xffff0000, v2
	v_and_b32_e32 v39, 0xffff0000, v10
	v_mul_f32_e32 v38, v142, v38
	v_mul_f32_e32 v39, v143, v39
	v_cvt_pk_bf16_f32 v38, v38, v39
	v_and_b32_e32 v39, 0xffff0000, v18
	v_mul_f32_e32 v39, v144, v39
	v_and_b32_e32 v41, 0xffff0000, v26
	v_mul_f32_e32 v41, v145, v41
	v_cvt_pk_bf16_f32 v39, v39, v41
	ds_write2_b64 v40, v[36:37], v[38:39] offset0:136 offset1:170
	v_and_b32_e32 v36, 0xffff, v6
	v_and_b32_e32 v37, 0xffff, v22
	v_lshrrev_b32_e32 v38, 16, v6
	v_lshrrev_b32_e32 v39, 16, v22
	v_lshl_or_b32 v36, v14, 16, v36
	v_lshl_or_b32 v37, v30, 16, v37
	v_and_or_b32 v38, v14, s33, v38
	v_and_or_b32 v39, v30, s33, v39
	ds_write2_b64 v148, v[36:37], v[38:39] offset0:136 offset1:170
	v_lshlrev_b32_e32 v36, 16, v3
	v_lshlrev_b32_e32 v37, 16, v11
	v_mul_f32_e32 v36, v142, v36
	v_mul_f32_e32 v37, v143, v37
	v_cvt_pk_bf16_f32 v36, v36, v37
	v_lshlrev_b32_e32 v37, 16, v19
	v_lshlrev_b32_e32 v38, 16, v27
	v_mul_f32_e32 v37, v144, v37
	v_mul_f32_e32 v38, v145, v38
	v_cvt_pk_bf16_f32 v37, v37, v38
	v_and_b32_e32 v38, 0xffff0000, v3
	v_and_b32_e32 v39, 0xffff0000, v11
	v_mul_f32_e32 v38, v142, v38
	v_mul_f32_e32 v39, v143, v39
	v_cvt_pk_bf16_f32 v38, v38, v39
	v_and_b32_e32 v39, 0xffff0000, v19
	v_mul_f32_e32 v39, v144, v39
	v_and_b32_e32 v41, 0xffff0000, v27
	v_mul_f32_e32 v41, v145, v41
	v_cvt_pk_bf16_f32 v39, v39, v41
	ds_write2_b64 v40, v[36:37], v[38:39] offset0:204 offset1:238
	v_and_b32_e32 v36, 0xffff, v7
	v_and_b32_e32 v37, 0xffff, v23
	v_lshrrev_b32_e32 v38, 16, v7
	v_lshrrev_b32_e32 v39, 16, v23
	v_lshl_or_b32 v36, v15, 16, v36
	v_lshl_or_b32 v37, v31, 16, v37
	v_and_or_b32 v38, v15, s33, v38
	v_and_or_b32 v39, v31, s33, v39
	ds_write2_b64 v148, v[36:37], v[38:39] offset0:204 offset1:238
	s_waitcnt vmcnt(1)
	v_mov_b64_e32 v[44:45], v[92:93]
	v_mov_b64_e32 v[36:37], v[88:89]
	v_mov_b64_e32 v[40:41], v[84:85]
	s_waitcnt vmcnt(0)
	v_mov_b64_e32 v[48:49], v[80:81]
	s_andn2_b64 vcc, exec, s[6:7]
	v_mov_b64_e32 v[46:47], v[94:95]
	v_mov_b64_e32 v[38:39], v[90:91]
	v_mov_b64_e32 v[42:43], v[86:87]
	v_mov_b64_e32 v[50:51], v[82:83]
	s_cbranch_vccnz .LBB0_666
	s_add_i32 s6, s17, s14
	s_lshl_b32 s6, s6, 7
	s_add_i32 s18, s6, s13
	v_or_b32_e32 v24, s18, v131
	v_mad_i64_i32 v[0:1], s[6:7], v24, s57, v[132:133]
	v_add_co_u32_e32 v4, vcc, 0x1000, v0
	v_or_b32_e32 v8, 1, v24
	s_nop 0
	v_addc_co_u32_e32 v5, vcc, 0, v1, vcc
	v_mad_i64_i32 v[8:9], s[6:7], v8, s57, v[132:133]
	v_add_co_u32_e32 v12, vcc, 0x1000, v8
	v_or_b32_e32 v16, 2, v24
	v_or_b32_e32 v24, 3, v24
	v_add_u32_e32 v38, s18, v146
	v_mov_b64_e32 v[36:37], s[34:35]
	v_addc_co_u32_e32 v13, vcc, 0, v9, vcc
	v_mad_i64_i32 v[16:17], s[6:7], v16, s57, v[132:133]
	v_mad_i64_i32 v[24:25], s[6:7], v24, s57, v[132:133]
	v_mad_i64_i32 v[36:37], s[6:7], v38, s57, v[36:37]
	v_add_co_u32_e32 v20, vcc, 0x1000, v16
	v_readlane_b32 s6, v253, 22
	s_nop 0
	v_addc_co_u32_e32 v21, vcc, 0, v17, vcc
	v_readlane_b32 s7, v253, 23
	v_add_co_u32_e32 v28, vcc, 0x1000, v24
	s_nop 0
	v_lshl_add_u64 v[36:37], v[36:37], 0, s[6:7]
	v_lshlrev_b32_e32 v128, 1, v134
	v_addc_co_u32_e32 v29, vcc, 0, v25, vcc
	v_lshl_add_u64 v[36:37], v[36:37], 0, v[128:129]
	s_mov_b64 s[6:7], 0x1200
	v_add_co_u32_e32 v44, vcc, s60, v36
	v_lshl_add_u64 v[48:49], v[36:37], 0, s[6:7]
	s_nop 0
	v_addc_co_u32_e32 v45, vcc, 0, v37, vcc
	global_load_dwordx4 v[0:3], v[4:5], off offset:1536
	global_load_dwordx4 v[4:7], v[4:5], off offset:2560
	global_load_dwordx4 v[8:11], v[12:13], off offset:1536
	global_load_dwordx4 v[12:15], v[12:13], off offset:2560
	global_load_dwordx4 v[16:19], v[20:21], off offset:1536
	global_load_dwordx4 v[20:23], v[20:21], off offset:2560
	global_load_dwordx4 v[24:27], v[28:29], off offset:1536
	global_load_dwordx4 v[28:31], v[28:29], off offset:2560
	global_load_dwordx4 v[36:39], v[48:49], off offset:64
	global_load_dwordx4 v[40:43], v[48:49], off offset:128
	global_load_dwordx4 v[44:47], v[44:45], off offset:512
	global_load_dwordx4 v[48:51], v[48:49], off offset:192
